# norm phases: also hoist the last (j=7) vector loads into reused registers and issue the batch before the preceding store (vmcnt(1))
# speedup vs baseline: 1.0059x; 1.0018x over previous
; __device__ __forceinline__ void norm_rows(const float* xl, const float* xc, const float* g, const float* modl, int sh_ofs, int sc_ofs, bf16_t* XN, int nrows, int gw, int NGW) {
;     ...
;     for (int row = gw; row < nrows; row += 2 * NGW) {
;         const int rowb = (row + NGW < nrows) ? row + NGW : row;
;         const f32x4* s4a = (const f32x4*)(row < RL ? xl + (size_t)row * DM : xc + (size_t)(row - RL) * DM) + lane;
;         const f32x4* s4b = (const f32x4*)(rowb < RL ? xl + (size_t)rowb * DM : xc + (size_t)(rowb - RL) * DM) + lane;
;         const int mia = row < RL ? (row >> 11) : 16, mib = rowb < RL ? (rowb >> 11) : 16;
;         f32x4 va[8], vb[8]; float ssa = 0.f, ssb = 0.f;
; #pragma unroll
;         for (int j = 0; j < 8; ++j) { va[j] = __builtin_nontemporal_load(s4a + 64 * j); vb[j] = __builtin_nontemporal_load(s4b + 64 * j); }
; #pragma unroll
;         for (int j = 0; j < 8; ++j) { ssa += (va[j][0] * va[j][0] + va[j][1] * va[j][1]) + (va[j][2] * va[j][2] + va[j][3] * va[j][3]); ssb += (vb[j][0] * vb[j][0] + vb[j][1] * vb[j][1]) + (vb[j][2] * vb[j][2] + vb[j][3] * vb[j][3]); }
;         const float rsa = rsqrtf(wave_sum(ssa) * (1.0f / DM) + EPS), rsb = rsqrtf(wave_sum(ssb) * (1.0f / DM) + EPS);
.LBB0_156:
	s_add_i32 s18, s46, 0xffff8000
	v_readlane_b32 s44, v255, 1
	v_readlane_b32 s45, v255, 2
	s_add_u32 s44, s44, s30
	s_addc_u32 s45, s45, s31
	s_cmp_lt_i32 s46, 0x8000
	global_load_dwordx4 v[56:59], v208, s[42:43] nt
	global_load_dwordx4 v[44:47], v208, s[42:43] offset:1024 nt
	global_load_dwordx4 v[40:43], v208, s[42:43] offset:2048 nt
	s_cselect_b32 s45, s45, 0
	s_cselect_b32 s44, s44, s18
	v_lshl_add_u64 v[0:1], s[42:43], 0, v[208:209]
	s_cselect_b32 s18, s17, s41
	s_cselect_b32 s47, s16, s40
	s_lshl_b64 s[44:45], s[44:45], 13
	v_add_co_u32_e32 v0, vcc, s96, v0
	s_add_u32 s44, s47, s44
	s_nop 0
	v_addc_co_u32_e32 v1, vcc, 0, v1, vcc
	s_addc_u32 s45, s18, s45
	global_load_dwordx4 v[24:27], v[0:1], off nt
	global_load_dwordx4 v[60:63], v208, s[44:45] nt
	global_load_dwordx4 v[52:55], v208, s[44:45] offset:1024 nt
	global_load_dwordx4 v[48:51], v208, s[44:45] offset:2048 nt
	global_load_dwordx4 v[36:39], v208, s[44:45] offset:3072 nt
	v_lshl_add_u64 v[2:3], s[44:45], 0, v[208:209]
	v_add_co_u32_e32 v4, vcc, s96, v2
	s_min_i32 s18, s46, 0x8000
	s_nop 0
	v_addc_co_u32_e32 v5, vcc, 0, v3, vcc
	global_load_dwordx4 v[28:31], v[4:5], off nt
	global_load_dwordx4 v[32:35], v208, s[42:43] offset:3072 nt
	global_load_dwordx4 v[20:23], v[4:5], off offset:1024 nt
	global_load_dwordx4 v[16:19], v[0:1], off offset:1024 nt
	global_load_dwordx4 v[8:11], v[0:1], off offset:2048 nt
	s_nop 0
	global_load_dwordx4 v[0:3], v[0:1], off offset:3072 nt
	s_nop 0
	global_load_dwordx4 v[12:15], v[4:5], off offset:2048 nt
	s_nop 0
	global_load_dwordx4 v[4:7], v[4:5], off offset:3072 nt
	s_min_i32 s42, s34, 0x8000
	s_ashr_i32 s18, s18, 11
	s_ashr_i32 s44, s42, 11
	s_mul_hi_i32 s43, s18, 0xc000
	s_mul_i32 s18, s18, 0xc000
	v_readlane_b32 s49, v255, 3
	s_add_u32 s42, s49, s18
	v_readlane_b32 s50, v255, 4
	s_addc_u32 s43, s50, s43
	v_lshl_add_u64 v[108:109], s[42:43], 0, v[208:209]
	s_mov_b32 s47, 0x9000
	s_movk_i32 s48, 0x7000
	s_mov_b32 s2, 0x3a000000
	s_mov_b32 s45, 0x800000
	s_mul_hi_i32 s18, s44, 0xc000
	s_mul_i32 s44, s44, 0xc000
	s_add_u32 s42, s49, s44
	s_addc_u32 s43, s50, s18
	s_lshl_b64 s[34:35], s[34:35], 12
	s_add_i32 s46, s46, s78
	s_add_u32 s30, s30, s78
	s_addc_u32 s31, s31, s79
	s_cmp_lt_i32 s46, s29
	s_waitcnt vmcnt(0)
	v_mov_b32_e32 v80, v57
	v_mov_b32_e32 v81, v45
	v_mov_b32_e32 v86, v59
	v_mov_b32_e32 v87, v47
	v_pk_mul_f32 v[94:95], v[42:43], v[42:43]
	v_pk_mul_f32 v[96:97], v[40:41], v[40:41]
	v_mov_b32_e32 v78, v56
	v_mov_b32_e32 v79, v44
	v_mov_b32_e32 v84, v58
	v_mov_b32_e32 v85, v46
	v_pk_mul_f32 v[80:81], v[80:81], v[80:81]
	v_pk_mul_f32 v[86:87], v[86:87], v[86:87]
	v_pk_mov_b32 v[98:99], v[96:97], v[94:95] op_sel:[1,0]
	v_mov_b32_e32 v97, v95
	v_pk_fma_f32 v[78:79], v[78:79], v[78:79], v[80:81]
	v_pk_fma_f32 v[80:81], v[84:85], v[84:85], v[86:87]
	v_pk_add_f32 v[84:85], v[98:99], v[96:97]
	v_mov_b32_e32 v86, v61
	v_mov_b32_e32 v87, v53
	v_mov_b32_e32 v96, v63
	v_mov_b32_e32 v97, v55
	v_pk_add_f32 v[78:79], v[78:79], v[80:81]
	v_mov_b32_e32 v80, v60
	v_mov_b32_e32 v81, v52
	v_mov_b32_e32 v94, v62
	v_mov_b32_e32 v95, v54
	v_pk_mul_f32 v[98:99], v[50:51], v[50:51]
	v_pk_mul_f32 v[100:101], v[48:49], v[48:49]
	v_pk_mul_f32 v[86:87], v[86:87], v[86:87]
	v_pk_mul_f32 v[96:97], v[96:97], v[96:97]
	v_pk_mov_b32 v[104:105], v[100:101], v[98:99] op_sel:[1,0]
	v_mov_b32_e32 v101, v99
	v_pk_fma_f32 v[80:81], v[80:81], v[80:81], v[86:87]
	v_pk_fma_f32 v[86:87], v[94:95], v[94:95], v[96:97]
	v_mul_f32_e32 v82, v37, v37
	v_mul_f32_e32 v102, v39, v39
	v_pk_add_f32 v[94:95], v[104:105], v[100:101]
	v_pk_add_f32 v[80:81], v[80:81], v[86:87]
	v_mul_f32_e32 v93, v24, v24
	v_mul_f32_e32 v106, v25, v25
	v_pk_fma_f32 v[98:99], v[36:37], v[36:37], v[82:83] op_sel_hi:[1,1,0]
	v_pk_fma_f32 v[102:103], v[38:39], v[38:39], v[102:103] op_sel_hi:[1,1,0]
	v_mul_f32_e32 v82, v28, v28
	v_mul_f32_e32 v96, v29, v29
	v_pk_add_f32 v[86:87], v[94:95], v[94:95] op_sel:[0,1] op_sel_hi:[1,0]
	v_pk_add_f32 v[80:81], v[80:81], v[80:81] op_sel:[0,1] op_sel_hi:[1,0]
	v_pk_add_f32 v[78:79], v[78:79], v[78:79] op_sel:[0,1] op_sel_hi:[1,0]
	v_pk_add_f32 v[84:85], v[84:85], v[84:85] op_sel:[0,1] op_sel_hi:[1,0]
	v_mul_f32_e32 v99, v30, v30
	v_mul_f32_e32 v103, v31, v31
	v_mov_b32_e32 v87, v96
	v_mov_b32_e32 v81, v82
	v_mov_b32_e32 v79, v93
	v_mov_b32_e32 v85, v106
	v_mul_f32_e32 v82, v33, v33
	v_pk_add_f32 v[94:95], v[98:99], v[102:103]
	v_pk_add_f32 v[80:81], v[80:81], v[86:87]
	v_pk_add_f32 v[78:79], v[78:79], v[84:85]
	v_pk_fma_f32 v[84:85], v[32:33], v[32:33], v[82:83] op_sel_hi:[1,1,0]
	v_mul_f32_e32 v82, v35, v35
	v_mul_f32_e32 v107, v26, v26
	v_pk_add_f32 v[80:81], v[80:81], v[94:95]
	v_mul_f32_e32 v94, v27, v27
	v_pk_fma_f32 v[86:87], v[34:35], v[34:35], v[82:83] op_sel_hi:[1,1,0]
	v_mov_b32_e32 v85, v107
	v_mov_b32_e32 v87, v94
	v_pk_add_f32 v[84:85], v[84:85], v[86:87]
	v_pk_mul_f32 v[86:87], v[20:21], v[20:21]
	v_pk_add_f32 v[78:79], v[78:79], v[84:85]
	v_pk_mul_f32 v[84:85], v[22:23], v[22:23]
	v_mul_f32_e32 v82, v4, v4
	v_pk_mov_b32 v[94:95], v[86:87], v[84:85] op_sel:[1,0]
	v_mov_b32_e32 v87, v85
	v_pk_add_f32 v[84:85], v[94:95], v[86:87]
	v_pk_mul_f32 v[86:87], v[18:19], v[18:19]
	v_pk_mul_f32 v[94:95], v[16:17], v[16:17]
	v_pk_add_f32 v[80:81], v[80:81], v[80:81] op_sel:[0,1] op_sel_hi:[1,0]
	v_pk_mov_b32 v[96:97], v[94:95], v[86:87] op_sel:[1,0]
	v_mul_f32_e32 v86, v5, v5
	v_pk_add_f32 v[84:85], v[84:85], v[84:85] op_sel:[0,1] op_sel_hi:[1,0]
	v_mov_b32_e32 v81, v82
	v_mov_b32_e32 v85, v86
	v_mul_f32_e32 v82, v13, v13
	v_mov_b32_e32 v95, v87
	v_mul_f32_e32 v87, v6, v6
	v_pk_add_f32 v[80:81], v[80:81], v[84:85]
	v_pk_fma_f32 v[84:85], v[12:13], v[12:13], v[82:83] op_sel_hi:[1,1,0]
	v_mul_f32_e32 v82, v15, v15
	v_mul_f32_e32 v93, v7, v7
	v_mov_b32_e32 v85, v87
	v_pk_fma_f32 v[86:87], v[14:15], v[14:15], v[82:83] op_sel_hi:[1,1,0]
	v_pk_add_f32 v[106:107], v[78:79], v[78:79] op_sel:[0,1] op_sel_hi:[1,0]
	v_mov_b32_e32 v87, v93
	v_add_co_u32_e32 v78, vcc, s47, v108
	v_pk_add_f32 v[84:85], v[84:85], v[86:87]
	s_nop 0
	v_addc_co_u32_e32 v79, vcc, 0, v109, vcc
	v_pk_add_f32 v[104:105], v[80:81], v[84:85]
	v_add_co_u32_e32 v80, vcc, s48, v108
	v_pk_add_f32 v[102:103], v[96:97], v[94:95]
	global_load_dwordx4 v[94:97], v[64:65], off
	global_load_dwordx4 v[84:87], v[78:79], off offset:-4096
	v_addc_co_u32_e32 v81, vcc, 0, v109, vcc
	global_load_dwordx4 v[98:101], v[80:81], off offset:-4096
	v_mul_f32_e32 v82, v0, v0
	v_mul_f32_e32 v93, v1, v1
	v_pk_add_f32 v[102:103], v[102:103], v[102:103] op_sel:[0,1] op_sel_hi:[1,0]
	v_mov_b32_e32 v107, v82
	v_mov_b32_e32 v103, v93
	v_mul_f32_e32 v82, v9, v9
	v_mul_f32_e32 v110, v2, v2
	v_pk_add_f32 v[102:103], v[106:107], v[102:103]
	v_pk_fma_f32 v[106:107], v[8:9], v[8:9], v[82:83] op_sel_hi:[1,1,0]
	v_mul_f32_e32 v82, v11, v11
	v_mul_f32_e32 v112, v3, v3
	v_mov_b32_e32 v107, v110
	v_pk_fma_f32 v[110:111], v[10:11], v[10:11], v[82:83] op_sel_hi:[1,1,0]
	s_waitcnt vmcnt(1)
; __device__ __forceinline__ unsigned cvt_pk_bf16(float lo, float hi) { unsigned r; asm volatile("v_cvt_pk_bf16_f32 %0, %1, %2" : "=v"(r) : "v"(lo), "v"(hi)); return r; }
; __device__ __forceinline__ void norm_rows(const float* xl, const float* xc, const float* g, const float* modl, int sh_ofs, int sc_ofs, bf16_t* XN, int nrows, int gw, int NGW) {
;     ...
;         const float rsa = rsqrtf(wave_sum(ssa) * (1.0f / DM) + EPS), rsb = rsqrtf(wave_sum(ssb) * (1.0f / DM) + EPS);
;         const f32x4* g4 = (const f32x4*)g + lane;
;         const f32x4* sca = (const f32x4*)(modl + (size_t)mia * 12288 + sc_ofs) + lane; const f32x4* sha = (const f32x4*)(modl + (size_t)mia * 12288 + sh_ofs) + lane;
;         const f32x4* scb = (const f32x4*)(modl + (size_t)mib * 12288 + sc_ofs) + lane; const f32x4* shb = (const f32x4*)(modl + (size_t)mib * 12288 + sh_ofs) + lane;
;         u32x2* oa = (u32x2*)(XN + (size_t)row * DM) + lane; u32x2* ob = (u32x2*)(XN + (size_t)rowb * DM) + lane;
; #pragma unroll
;         for (int j = 0; j < 8; ++j) { const f32x4 gj = g4[64 * j];
;             const f32x4 ya = va[j] * rsa * gj * (sca[64 * j] + 1.0f) + sha[64 * j]; u32x2 w; w.x = cvt_pk_bf16(ya[0], ya[1]); w.y = cvt_pk_bf16(ya[2], ya[3]); oa[64 * j] = w;
	v_pk_add_f32 v[84:85], v[84:85], 1.0 op_sel_hi:[1,0]
	v_mov_b32_e32 v111, v112
	v_pk_add_f32 v[106:107], v[106:107], v[110:111]
	v_lshl_add_u64 v[110:111], s[42:43], 0, v[208:209]
	v_pk_add_f32 v[102:103], v[102:103], v[106:107]
	v_mov_b32_e32 v107, v104
	v_mov_b32_e32 v106, v102
	v_mov_b32_e32 v104, v103
	v_pk_add_f32 v[102:103], v[106:107], v[104:105]
	ds_bpermute_b32 v105, v83, v103
	ds_bpermute_b32 v104, v83, v102
	v_pk_add_f32 v[86:87], v[86:87], 1.0 op_sel_hi:[1,0]
	s_mov_b64 s[42:43], 0x6000
	s_waitcnt lgkmcnt(0)
	v_pk_add_f32 v[102:103], v[102:103], v[104:105]
	ds_bpermute_b32 v105, v88, v103
	ds_bpermute_b32 v104, v88, v102
	s_waitcnt lgkmcnt(0)
	v_pk_add_f32 v[102:103], v[102:103], v[104:105]
	ds_bpermute_b32 v105, v89, v103
	ds_bpermute_b32 v104, v89, v102
	s_waitcnt lgkmcnt(0)
	v_pk_add_f32 v[102:103], v[102:103], v[104:105]
	ds_bpermute_b32 v105, v90, v103
	ds_bpermute_b32 v104, v90, v102
	s_waitcnt lgkmcnt(0)
	v_pk_add_f32 v[102:103], v[102:103], v[104:105]
	ds_bpermute_b32 v105, v91, v103
	ds_bpermute_b32 v104, v91, v102
	s_waitcnt lgkmcnt(0)
	v_pk_add_f32 v[102:103], v[102:103], v[104:105]
	ds_bpermute_b32 v105, v92, v103
	ds_bpermute_b32 v104, v92, v102
	s_waitcnt lgkmcnt(0)
	v_pk_add_f32 v[102:103], v[102:103], v[104:105]
	s_nop 0
	v_pk_fma_f32 v[106:107], v[102:103], s[2:3], v[238:239] op_sel_hi:[1,0,0]
	s_nop 0
	v_mul_f32_e32 v82, 0x4b800000, v107
	v_cmp_gt_f32_e32 vcc, s45, v107
	s_nop 1
	v_cndmask_b32_e32 v82, v107, v82, vcc
	v_rsq_f32_e32 v82, v82
	s_nop 0
	v_mul_f32_e32 v93, 0x45800000, v82
	v_cndmask_b32_e32 v82, v82, v93, vcc
	v_pk_mul_f32 v[60:61], v[60:61], v[82:83] op_sel_hi:[1,0]
	v_pk_mul_f32 v[62:63], v[62:63], v[82:83] op_sel_hi:[1,0]
	v_pk_mul_f32 v[60:61], v[94:95], v[60:61]
	v_pk_mul_f32 v[62:63], v[96:97], v[62:63]
	s_waitcnt vmcnt(0)
	v_pk_fma_f32 v[60:61], v[84:85], v[60:61], v[98:99]
	v_add_co_u32_e32 v84, vcc, s47, v110
	v_pk_fma_f32 v[62:63], v[86:87], v[62:63], v[100:101]
	s_nop 0
	v_addc_co_u32_e32 v85, vcc, 0, v111, vcc
	v_cvt_pk_bf16_f32 v60, v60, v61
	v_cvt_pk_bf16_f32 v61, v62, v63
	global_store_dwordx2 v[76:77], v[60:61], off
	v_add_co_u32_e32 v86, vcc, s48, v110
	global_load_dwordx4 v[98:101], v[84:85], off offset:-4096
	s_nop 0
	v_addc_co_u32_e32 v87, vcc, 0, v111, vcc
	global_load_dwordx4 v[102:105], v[86:87], off offset:-4096
	v_mul_f32_e32 v60, 0x4b800000, v106
	v_cmp_gt_f32_e32 vcc, s45, v106
	v_pk_mul_f32 v[52:53], v[52:53], v[82:83] op_sel_hi:[1,0]
	v_pk_mul_f32 v[54:55], v[54:55], v[82:83] op_sel_hi:[1,0]
	v_cndmask_b32_e32 v60, v106, v60, vcc
	v_rsq_f32_e32 v60, v60
	v_pk_mul_f32 v[48:49], v[48:49], v[82:83] op_sel_hi:[1,0]
	v_pk_mul_f32 v[50:51], v[50:51], v[82:83] op_sel_hi:[1,0]
	v_pk_mul_f32 v[36:37], v[36:37], v[82:83] op_sel_hi:[1,0]
	v_mul_f32_e32 v61, 0x45800000, v60
	v_cndmask_b32_e32 v62, v60, v61, vcc
	v_pk_mul_f32 v[58:59], v[58:59], v[62:63] op_sel_hi:[1,0]
	v_pk_mul_f32 v[56:57], v[56:57], v[62:63] op_sel_hi:[1,0]
	v_pk_mul_f32 v[58:59], v[96:97], v[58:59]
	v_pk_mul_f32 v[56:57], v[94:95], v[56:57]
	v_lshl_add_u64 v[60:61], v[66:67], 0, s[34:35]
	s_mov_b64 s[34:35], 0x8000
	v_lshl_add_u64 v[106:107], v[110:111], 0, s[34:35]
	v_pk_mul_f32 v[44:45], v[44:45], v[62:63] op_sel_hi:[1,0]
	v_pk_mul_f32 v[46:47], v[46:47], v[62:63] op_sel_hi:[1,0]
	v_pk_mul_f32 v[42:43], v[42:43], v[62:63] op_sel_hi:[1,0]
	v_pk_mul_f32 v[40:41], v[40:41], v[62:63] op_sel_hi:[1,0]
	v_pk_mul_f32 v[38:39], v[38:39], v[82:83] op_sel_hi:[1,0]
	v_pk_mul_f32 v[32:33], v[32:33], v[62:63] op_sel_hi:[1,0]
	v_pk_mul_f32 v[34:35], v[34:35], v[62:63] op_sel_hi:[1,0]
	v_pk_mul_f32 v[28:29], v[28:29], v[82:83] op_sel_hi:[1,0]
	v_pk_mul_f32 v[30:31], v[30:31], v[82:83] op_sel_hi:[1,0]
	v_pk_mul_f32 v[24:25], v[24:25], v[62:63] op_sel_hi:[1,0]
	v_pk_mul_f32 v[26:27], v[26:27], v[62:63] op_sel_hi:[1,0]
	v_pk_mul_f32 v[20:21], v[20:21], v[82:83] op_sel_hi:[1,0]
	v_pk_mul_f32 v[22:23], v[22:23], v[82:83] op_sel_hi:[1,0]
	v_pk_mul_f32 v[16:17], v[16:17], v[62:63] op_sel_hi:[1,0]
	v_pk_mul_f32 v[18:19], v[18:19], v[62:63] op_sel_hi:[1,0]
	v_pk_mul_f32 v[12:13], v[12:13], v[82:83] op_sel_hi:[1,0]
	v_pk_mul_f32 v[14:15], v[14:15], v[82:83] op_sel_hi:[1,0]
	v_pk_mul_f32 v[8:9], v[8:9], v[62:63] op_sel_hi:[1,0]
	v_pk_mul_f32 v[10:11], v[10:11], v[62:63] op_sel_hi:[1,0]
	v_pk_mul_f32 v[4:5], v[4:5], v[82:83] op_sel_hi:[1,0]
	v_pk_mul_f32 v[6:7], v[6:7], v[82:83] op_sel_hi:[1,0]
	v_pk_mul_f32 v[0:1], v[0:1], v[62:63] op_sel_hi:[1,0]
	v_pk_mul_f32 v[2:3], v[2:3], v[62:63] op_sel_hi:[1,0]
	s_waitcnt vmcnt(1)
	v_pk_add_f32 v[96:97], v[98:99], 1.0 op_sel_hi:[1,0]
	v_pk_add_f32 v[94:95], v[100:101], 1.0 op_sel_hi:[1,0]
	s_waitcnt vmcnt(0)
; __device__ __forceinline__ unsigned cvt_pk_bf16(float lo, float hi) { unsigned r; asm volatile("v_cvt_pk_bf16_f32 %0, %1, %2" : "=v"(r) : "v"(lo), "v"(hi)); return r; }
; __device__ __forceinline__ void norm_rows(const float* xl, const float* xc, const float* g, const float* modl, int sh_ofs, int sc_ofs, bf16_t* XN, int nrows, int gw, int NGW) {
;     ...
;         const f32x4* sca = (const f32x4*)(modl + (size_t)mia * 12288 + sc_ofs) + lane; const f32x4* sha = (const f32x4*)(modl + (size_t)mia * 12288 + sh_ofs) + lane;
;         const f32x4* scb = (const f32x4*)(modl + (size_t)mib * 12288 + sc_ofs) + lane; const f32x4* shb = (const f32x4*)(modl + (size_t)mib * 12288 + sh_ofs) + lane;
;         u32x2* oa = (u32x2*)(XN + (size_t)row * DM) + lane; u32x2* ob = (u32x2*)(XN + (size_t)rowb * DM) + lane;
; #pragma unroll
;         for (int j = 0; j < 8; ++j) { const f32x4 gj = g4[64 * j];
;             const f32x4 ya = va[j] * rsa * gj * (sca[64 * j] + 1.0f) + sha[64 * j]; u32x2 w; w.x = cvt_pk_bf16(ya[0], ya[1]); w.y = cvt_pk_bf16(ya[2], ya[3]); oa[64 * j] = w;
;             const f32x4 yb = vb[j] * rsb * gj * (scb[64 * j] + 1.0f) + shb[64 * j]; u32x2 w2; w2.x = cvt_pk_bf16(yb[0], yb[1]); w2.y = cvt_pk_bf16(yb[2], yb[3]); ob[64 * j] = w2; }
	v_pk_fma_f32 v[56:57], v[96:97], v[56:57], v[102:103]
	v_pk_fma_f32 v[58:59], v[94:95], v[58:59], v[104:105]
	v_cvt_pk_bf16_f32 v56, v56, v57
	v_lshl_add_u64 v[102:103], v[108:109], 0, s[34:35]
	v_cvt_pk_bf16_f32 v57, v58, v59
	v_lshl_add_u64 v[250:251], v[108:109], 0, s[42:43]
	v_lshl_add_u64 v[240:241], v[110:111], 0, s[42:43]
	global_load_dwordx4 v[116:119], v[64:65], off offset:1024
	global_load_dwordx4 v[120:123], v[102:103], off offset:1024
	global_load_dwordx4 v[124:127], v[250:251], off offset:1024
	global_load_dwordx4 v[128:131], v[106:107], off offset:1024
	global_load_dwordx4 v[132:135], v[240:241], off offset:1024
	global_load_dwordx4 v[136:139], v[64:65], off offset:2048
	global_load_dwordx4 v[140:143], v[102:103], off offset:2048
	global_load_dwordx4 v[144:147], v[250:251], off offset:2048
	global_load_dwordx4 v[148:151], v[106:107], off offset:2048
	global_load_dwordx4 v[152:155], v[240:241], off offset:2048
	global_load_dwordx4 v[156:159], v[64:65], off offset:3072
	global_load_dwordx4 v[160:163], v[102:103], off offset:3072
	global_load_dwordx4 v[164:167], v[250:251], off offset:3072
	global_load_dwordx4 v[168:171], v[106:107], off offset:3072
	global_load_dwordx4 v[172:175], v[240:241], off offset:3072
	global_load_dwordx4 v[176:179], v[68:69], off
	global_load_dwordx4 v[180:183], v[78:79], off
	global_load_dwordx4 v[184:187], v[80:81], off
	global_load_dwordx4 v[188:191], v[84:85], off
	global_load_dwordx4 v[192:195], v[86:87], off
	global_load_dwordx4 v[196:199], v[70:71], off
	global_load_dwordx4 v[200:203], v[78:79], off offset:1024
	global_load_dwordx4 v[204:207], v[80:81], off offset:1024
	global_load_dwordx4 v[210:213], v[84:85], off offset:1024
	global_load_dwordx4 v[218:221], v[86:87], off offset:1024
	global_load_dwordx4 v[222:225], v[72:73], off
	global_load_dwordx4 v[226:229], v[78:79], off offset:2048
	global_load_dwordx4 v[230:233], v[80:81], off offset:2048
	global_load_dwordx4 v[234:237], v[84:85], off offset:2048
	global_load_dwordx4 v[246:249], v[86:87], off offset:2048
	global_store_dwordx2 v[60:61], v[56:57], off
	s_waitcnt vmcnt(1)
	s_nop 0
	v_lshl_add_u64 v[104:105], v[108:109], 0, s[42:43]
	s_nop 0
	s_nop 0
	v_readlane_b32 s34, v254, 45
	v_readlane_b32 s35, v254, 46
	s_nop 0
	v_pk_mul_f32 v[52:53], v[52:53], v[116:117]
	v_pk_mul_f32 v[54:55], v[54:55], v[118:119]
	s_nop 0
	v_pk_add_f32 v[94:95], v[120:121], 1.0 op_sel_hi:[1, 0]
	v_pk_add_f32 v[96:97], v[122:123], 1.0 op_sel_hi:[1, 0]
	s_nop 0
	v_pk_fma_f32 v[52:53], v[52:53], v[94:95], v[124:125]
	v_pk_fma_f32 v[54:55], v[54:55], v[96:97], v[126:127]
	v_cvt_pk_bf16_f32 v52, v52, v53
	v_lshl_add_u64 v[98:99], v[110:111], 0, s[42:43]
	v_cvt_pk_bf16_f32 v53, v54, v55
	global_store_dwordx2 v[76:77], v[52:53], off offset:512
	s_nop 0
	v_pk_mul_f32 v[44:45], v[116:117], v[44:45]
	s_nop 0
	v_pk_mul_f32 v[46:47], v[118:119], v[46:47]
	s_nop 0
	v_pk_add_f32 v[52:53], v[128:129], 1.0 op_sel_hi:[1, 0]
	v_pk_add_f32 v[54:55], v[130:131], 1.0 op_sel_hi:[1, 0]
	s_nop 0
	v_pk_fma_f32 v[44:45], v[44:45], v[52:53], v[132:133]
	v_pk_fma_f32 v[46:47], v[46:47], v[54:55], v[134:135]
	v_cvt_pk_bf16_f32 v44, v44, v45
	s_nop 0
	v_cvt_pk_bf16_f32 v45, v46, v47
	global_store_dwordx2 v[60:61], v[44:45], off offset:512
	global_load_dwordx4 v[116:119], v[74:75], off
	global_load_dwordx4 v[120:123], v[78:79], off offset:3072
	global_load_dwordx4 v[124:127], v[80:81], off offset:3072
	global_load_dwordx4 v[128:131], v[84:85], off offset:3072
	global_load_dwordx4 v[132:135], v[86:87], off offset:3072
	s_nop 0
	s_nop 0
	s_nop 0
	s_nop 0
	s_nop 0
	v_pk_mul_f32 v[48:49], v[48:49], v[136:137]
	s_nop 0
	v_pk_add_f32 v[52:53], v[140:141], 1.0 op_sel_hi:[1, 0]
	v_pk_mul_f32 v[50:51], v[50:51], v[138:139]
	v_pk_add_f32 v[54:55], v[142:143], 1.0 op_sel_hi:[1, 0]
	s_nop 0
	v_pk_fma_f32 v[48:49], v[48:49], v[52:53], v[144:145]
	v_pk_fma_f32 v[50:51], v[50:51], v[54:55], v[146:147]
	v_cvt_pk_bf16_f32 v48, v48, v49
	v_pk_mul_f32 v[40:41], v[40:41], v[136:137]
	v_cvt_pk_bf16_f32 v49, v50, v51
	global_store_dwordx2 v[76:77], v[48:49], off offset:1024
	s_nop 0
	s_nop 0
	s_nop 0
	v_pk_mul_f32 v[42:43], v[42:43], v[138:139]
	s_nop 0
	v_pk_add_f32 v[46:47], v[148:149], 1.0 op_sel_hi:[1, 0]
	v_pk_add_f32 v[44:45], v[150:151], 1.0 op_sel_hi:[1, 0]
	s_nop 0
	v_pk_fma_f32 v[40:41], v[40:41], v[46:47], v[152:153]
	v_pk_fma_f32 v[42:43], v[42:43], v[44:45], v[154:155]
	v_cvt_pk_bf16_f32 v40, v40, v41
	s_nop 0
	v_cvt_pk_bf16_f32 v41, v42, v43
	global_store_dwordx2 v[60:61], v[40:41], off offset:1024
	s_nop 0
	s_nop 0
	s_nop 0
	s_nop 0
	s_nop 0
	v_pk_mul_f32 v[36:37], v[36:37], v[156:157]
	s_nop 0
	v_pk_add_f32 v[44:45], v[160:161], 1.0 op_sel_hi:[1, 0]
	v_pk_mul_f32 v[38:39], v[38:39], v[158:159]
	v_pk_add_f32 v[46:47], v[162:163], 1.0 op_sel_hi:[1, 0]
; __device__ __forceinline__ unsigned cvt_pk_bf16(float lo, float hi) { unsigned r; asm volatile("v_cvt_pk_bf16_f32 %0, %1, %2" : "=v"(r) : "v"(lo), "v"(hi)); return r; }
; __device__ __forceinline__ void norm_rows(const float* xl, const float* xc, const float* g, const float* modl, int sh_ofs, int sc_ofs, bf16_t* XN, int nrows, int gw, int NGW) {
;     ...
;         for (int j = 0; j < 8; ++j) { const f32x4 gj = g4[64 * j];
;             const f32x4 ya = va[j] * rsa * gj * (sca[64 * j] + 1.0f) + sha[64 * j]; u32x2 w; w.x = cvt_pk_bf16(ya[0], ya[1]); w.y = cvt_pk_bf16(ya[2], ya[3]); oa[64 * j] = w;
;             const f32x4 yb = vb[j] * rsb * gj * (scb[64 * j] + 1.0f) + shb[64 * j]; u32x2 w2; w2.x = cvt_pk_bf16(yb[0], yb[1]); w2.y = cvt_pk_bf16(yb[2], yb[3]); ob[64 * j] = w2; }
	s_nop 0
	v_pk_fma_f32 v[36:37], v[36:37], v[44:45], v[164:165]
	v_pk_fma_f32 v[38:39], v[38:39], v[46:47], v[166:167]
	v_cvt_pk_bf16_f32 v36, v36, v37
	v_pk_mul_f32 v[32:33], v[32:33], v[156:157]
	v_cvt_pk_bf16_f32 v37, v38, v39
	global_store_dwordx2 v[76:77], v[36:37], off offset:1536
	s_nop 0
	s_nop 0
	s_nop 0
	v_pk_mul_f32 v[34:35], v[34:35], v[158:159]
	s_nop 0
	v_pk_add_f32 v[36:37], v[168:169], 1.0 op_sel_hi:[1, 0]
	v_pk_add_f32 v[38:39], v[170:171], 1.0 op_sel_hi:[1, 0]
	s_nop 0
	v_pk_fma_f32 v[32:33], v[32:33], v[36:37], v[172:173]
	v_pk_fma_f32 v[34:35], v[34:35], v[38:39], v[174:175]
	v_cvt_pk_bf16_f32 v32, v32, v33
	s_nop 0
	v_cvt_pk_bf16_f32 v33, v34, v35
	global_store_dwordx2 v[60:61], v[32:33], off offset:1536
	s_nop 0
	s_nop 0
	s_nop 0
	s_nop 0
	s_nop 0
	v_pk_mul_f32 v[28:29], v[28:29], v[176:177]
	s_nop 0
	v_pk_add_f32 v[36:37], v[180:181], 1.0 op_sel_hi:[1, 0]
	v_pk_mul_f32 v[30:31], v[30:31], v[178:179]
	v_pk_add_f32 v[38:39], v[182:183], 1.0 op_sel_hi:[1, 0]
	s_nop 0
	v_pk_fma_f32 v[28:29], v[28:29], v[36:37], v[184:185]
	v_pk_fma_f32 v[30:31], v[30:31], v[38:39], v[186:187]
	v_cvt_pk_bf16_f32 v28, v28, v29
	v_pk_mul_f32 v[24:25], v[24:25], v[176:177]
	v_cvt_pk_bf16_f32 v29, v30, v31
	global_store_dwordx2 v[76:77], v[28:29], off offset:2048
	s_nop 0
	s_nop 0
	s_nop 0
	v_pk_mul_f32 v[26:27], v[26:27], v[178:179]
	s_nop 0
	v_pk_add_f32 v[28:29], v[188:189], 1.0 op_sel_hi:[1, 0]
	v_pk_add_f32 v[30:31], v[190:191], 1.0 op_sel_hi:[1, 0]
	s_nop 0
	v_pk_fma_f32 v[24:25], v[24:25], v[28:29], v[192:193]
	v_pk_fma_f32 v[26:27], v[26:27], v[30:31], v[194:195]
	v_cvt_pk_bf16_f32 v24, v24, v25
	s_nop 0
	v_cvt_pk_bf16_f32 v25, v26, v27
	global_store_dwordx2 v[60:61], v[24:25], off offset:2048
	s_nop 0
	s_nop 0
	s_nop 0
	s_nop 0
	s_nop 0
	v_pk_mul_f32 v[20:21], v[20:21], v[196:197]
	s_nop 0
	v_pk_add_f32 v[28:29], v[200:201], 1.0 op_sel_hi:[1, 0]
	v_pk_mul_f32 v[22:23], v[22:23], v[198:199]
	v_pk_add_f32 v[30:31], v[202:203], 1.0 op_sel_hi:[1, 0]
	s_nop 0
	v_pk_fma_f32 v[20:21], v[20:21], v[28:29], v[204:205]
	v_pk_fma_f32 v[22:23], v[22:23], v[30:31], v[206:207]
	v_cvt_pk_bf16_f32 v20, v20, v21
	v_pk_mul_f32 v[16:17], v[16:17], v[196:197]
	v_cvt_pk_bf16_f32 v21, v22, v23
	global_store_dwordx2 v[76:77], v[20:21], off offset:2560
	s_nop 0
	s_nop 0
	s_nop 0
	v_pk_mul_f32 v[18:19], v[18:19], v[198:199]
	s_nop 0
	v_pk_add_f32 v[20:21], v[210:211], 1.0 op_sel_hi:[1, 0]
	v_pk_add_f32 v[22:23], v[212:213], 1.0 op_sel_hi:[1, 0]
	s_nop 0
	v_pk_fma_f32 v[16:17], v[16:17], v[20:21], v[218:219]
	v_pk_fma_f32 v[18:19], v[18:19], v[22:23], v[220:221]
	v_cvt_pk_bf16_f32 v16, v16, v17
	s_nop 0
	v_cvt_pk_bf16_f32 v17, v18, v19
	global_store_dwordx2 v[60:61], v[16:17], off offset:2560
	s_nop 0
	s_nop 0
	s_nop 0
	s_nop 0
	s_nop 0
	v_pk_mul_f32 v[12:13], v[12:13], v[222:223]
	s_nop 0
	v_pk_add_f32 v[20:21], v[226:227], 1.0 op_sel_hi:[1, 0]
	v_pk_mul_f32 v[14:15], v[14:15], v[224:225]
	v_pk_add_f32 v[22:23], v[228:229], 1.0 op_sel_hi:[1, 0]
	s_nop 0
	v_pk_fma_f32 v[12:13], v[12:13], v[20:21], v[230:231]
	v_pk_fma_f32 v[14:15], v[14:15], v[22:23], v[232:233]
	v_cvt_pk_bf16_f32 v12, v12, v13
	v_pk_mul_f32 v[8:9], v[8:9], v[222:223]
	v_cvt_pk_bf16_f32 v13, v14, v15
	global_store_dwordx2 v[76:77], v[12:13], off offset:3072
	s_nop 0
	s_nop 0
	s_nop 0
	v_pk_mul_f32 v[10:11], v[10:11], v[224:225]
	s_nop 0
	v_pk_add_f32 v[12:13], v[234:235], 1.0 op_sel_hi:[1, 0]
	v_pk_add_f32 v[14:15], v[236:237], 1.0 op_sel_hi:[1, 0]
	s_nop 0
	v_pk_fma_f32 v[8:9], v[8:9], v[12:13], v[246:247]
	v_pk_fma_f32 v[10:11], v[10:11], v[14:15], v[248:249]
	v_cvt_pk_bf16_f32 v8, v8, v9
	s_nop 0
	v_cvt_pk_bf16_f32 v9, v10, v11
	global_store_dwordx2 v[60:61], v[8:9], off offset:3072
	s_nop 0
	s_nop 0
	s_nop 0
	s_nop 0
	s_waitcnt vmcnt(0)
	v_pk_mul_f32 v[4:5], v[4:5], v[116:117]
	s_nop 0
	v_pk_add_f32 v[12:13], v[120:121], 1.0 op_sel_hi:[1, 0]
	v_pk_mul_f32 v[6:7], v[6:7], v[118:119]
	v_pk_add_f32 v[14:15], v[122:123], 1.0 op_sel_hi:[1, 0]
	s_nop 0
	v_pk_fma_f32 v[4:5], v[4:5], v[12:13], v[124:125]
	v_pk_fma_f32 v[6:7], v[6:7], v[14:15], v[126:127]
	v_cvt_pk_bf16_f32 v4, v4, v5
	v_pk_mul_f32 v[0:1], v[0:1], v[116:117]
	v_cvt_pk_bf16_f32 v5, v6, v7
	global_store_dwordx2 v[76:77], v[4:5], off offset:3584
	s_nop 0
	s_nop 0
	s_nop 0
	v_pk_mul_f32 v[2:3], v[2:3], v[118:119]
	v_lshl_add_u64 v[76:77], v[76:77], 0, s[34:35]
	s_nop 0
	v_pk_add_f32 v[4:5], v[128:129], 1.0 op_sel_hi:[1, 0]
	v_pk_add_f32 v[6:7], v[130:131], 1.0 op_sel_hi:[1, 0]
	s_nop 0
	v_pk_fma_f32 v[0:1], v[0:1], v[4:5], v[132:133]
	v_pk_fma_f32 v[2:3], v[2:3], v[6:7], v[134:135]
	v_cvt_pk_bf16_f32 v0, v0, v1
	s_nop 0
	v_cvt_pk_bf16_f32 v1, v2, v3
	global_store_dwordx2 v[60:61], v[0:1], off offset:3584
	s_cbranch_scc0 .LBB0_161

; __device__ __forceinline__ void norm_rows(const float* xl, const float* xc, const float* g, const float* modl, int sh_ofs, int sc_ofs, bf16_t* XN, int nrows, int gw, int NGW) {
;     ...
;     for (int row = gw; row < nrows; row += 2 * NGW) {
;         const int rowb = (row + NGW < nrows) ? row + NGW : row;
;         const f32x4* s4a = (const f32x4*)(row < RL ? xl + (size_t)row * DM : xc + (size_t)(row - RL) * DM) + lane;
;         const f32x4* s4b = (const f32x4*)(rowb < RL ? xl + (size_t)rowb * DM : xc + (size_t)(rowb - RL) * DM) + lane;
;         const int mia = row < RL ? (row >> 11) : 16, mib = rowb < RL ? (rowb >> 11) : 16;
;         f32x4 va[8], vb[8]; float ssa = 0.f, ssb = 0.f;
; #pragma unroll
;         for (int j = 0; j < 8; ++j) { va[j] = __builtin_nontemporal_load(s4a + 64 * j); vb[j] = __builtin_nontemporal_load(s4b + 64 * j); }
; #pragma unroll
;         for (int j = 0; j < 8; ++j) { ssa += (va[j][0] * va[j][0] + va[j][1] * va[j][1]) + (va[j][2] * va[j][2] + va[j][3] * va[j][3]); ssb += (vb[j][0] * vb[j][0] + vb[j][1] * vb[j][1]) + (vb[j][2] * vb[j][2] + vb[j][3] * vb[j][3]); }
;         const float rsa = rsqrtf(wave_sum(ssa) * (1.0f / DM) + EPS), rsb = rsqrtf(wave_sum(ssb) * (1.0f / DM) + EPS);
.LBB0_501:
	s_add_i32 s18, s30, 0xffff8000
	s_mov_b64 s[28:29], s[42:43]
	s_add_u32 s28, s28, s0
	s_addc_u32 s29, s29, s1
	s_cmp_lt_i32 s30, 0x8000
	v_readlane_b32 s34, v254, 63
	s_cselect_b32 s29, s29, 0
	s_cselect_b32 s28, s28, s18
	v_readlane_b32 s35, v255, 0
	global_load_dwordx4 v[56:59], v208, s[16:17] nt
	global_load_dwordx4 v[48:51], v208, s[16:17] offset:1024 nt
	global_load_dwordx4 v[40:43], v208, s[16:17] offset:2048 nt
	s_cselect_b32 s18, s41, s35
	s_cselect_b32 s31, s40, s34
	s_lshl_b64 s[28:29], s[28:29], 13
	s_add_u32 s28, s31, s28
	s_addc_u32 s29, s18, s29
	v_lshl_add_u64 v[0:1], s[28:29], 0, v[208:209]
	global_load_dwordx4 v[60:63], v208, s[28:29] nt
	global_load_dwordx4 v[52:55], v208, s[28:29] offset:1024 nt
	global_load_dwordx4 v[44:47], v208, s[28:29] offset:2048 nt
	global_load_dwordx4 v[32:35], v208, s[28:29] offset:3072 nt
	v_add_co_u32_e32 v24, vcc, s96, v0
	v_readlane_b32 s28, v255, 3
	s_nop 0
	v_addc_co_u32_e32 v25, vcc, 0, v1, vcc
	global_load_dwordx4 v[20:23], v[24:25], off nt
	v_lshl_add_u64 v[0:1], s[16:17], 0, v[208:209]
	v_add_co_u32_e32 v0, vcc, s96, v0
	v_readlane_b32 s31, v255, 4
	s_nop 0
	v_addc_co_u32_e32 v1, vcc, 0, v1, vcc
	global_load_dwordx4 v[16:19], v[0:1], off nt
	global_load_dwordx4 v[28:31], v208, s[16:17] offset:3072 nt
	global_load_dwordx4 v[8:11], v[0:1], off offset:1024 nt
	global_load_dwordx4 v[4:7], v[0:1], off offset:2048 nt
	s_nop 0
	global_load_dwordx4 v[0:3], v[0:1], off offset:3072 nt
	s_min_i32 s16, s30, 0x8000
	global_load_dwordx4 v[12:15], v[24:25], off offset:1024 nt
	global_load_dwordx4 v[36:39], v[24:25], off offset:2048 nt
	s_nop 0
	global_load_dwordx4 v[24:27], v[24:25], off offset:3072 nt
	s_min_i32 s17, s14, 0x8000
	s_ashr_i32 s16, s16, 11
	s_ashr_i32 s18, s17, 11
	s_mul_hi_i32 s17, s16, 0xc000
	s_mul_i32 s16, s16, 0xc000
	s_add_u32 s16, s28, s16
	s_addc_u32 s17, s31, s17
	global_load_dwordx4 v[94:97], v208, s[16:17]
	s_mov_b32 s2, 0x3a000000
	s_mul_hi_i32 s29, s18, 0xc000
	s_mul_i32 s18, s18, 0xc000
	s_add_u32 s28, s28, s18
	s_addc_u32 s29, s31, s29
	s_lshl_b64 s[14:15], s[14:15], 12
	s_add_i32 s30, s30, s78
	s_add_u32 s0, s0, s78
	s_addc_u32 s1, s1, s79
	s_cmp_gt_i32 s30, 0x8fff
	s_waitcnt vmcnt(0)
	v_mov_b32_e32 v82, v57
	v_mov_b32_e32 v83, v49
	v_mov_b32_e32 v86, v59
	v_mov_b32_e32 v87, v51
	v_pk_mul_f32 v[98:99], v[42:43], v[42:43]
	v_pk_mul_f32 v[100:101], v[40:41], v[40:41]
	v_mov_b32_e32 v78, v56
	v_mov_b32_e32 v79, v48
	v_mov_b32_e32 v84, v58
	v_mov_b32_e32 v85, v50
	v_pk_mul_f32 v[82:83], v[82:83], v[82:83]
	v_pk_mul_f32 v[86:87], v[86:87], v[86:87]
	v_pk_mov_b32 v[102:103], v[100:101], v[98:99] op_sel:[1,0]
	v_mov_b32_e32 v101, v99
	v_pk_fma_f32 v[78:79], v[78:79], v[78:79], v[82:83]
	v_pk_fma_f32 v[82:83], v[84:85], v[84:85], v[86:87]
	v_pk_add_f32 v[84:85], v[102:103], v[100:101]
	v_mov_b32_e32 v86, v61
	v_mov_b32_e32 v87, v53
	v_mov_b32_e32 v100, v63
	v_mov_b32_e32 v101, v55
	v_pk_add_f32 v[78:79], v[78:79], v[82:83]
	v_mov_b32_e32 v82, v60
	v_mov_b32_e32 v83, v52
	v_mov_b32_e32 v98, v62
	v_mov_b32_e32 v99, v54
	v_pk_mul_f32 v[102:103], v[46:47], v[46:47]
	v_pk_mul_f32 v[104:105], v[44:45], v[44:45]
	v_pk_mul_f32 v[86:87], v[86:87], v[86:87]
	v_pk_mul_f32 v[100:101], v[100:101], v[100:101]
	v_pk_mov_b32 v[108:109], v[104:105], v[102:103] op_sel:[1,0]
	v_mov_b32_e32 v105, v103
	v_pk_fma_f32 v[82:83], v[82:83], v[82:83], v[86:87]
	v_pk_fma_f32 v[86:87], v[98:99], v[98:99], v[100:101]
	v_mul_f32_e32 v80, v33, v33
	v_pk_add_f32 v[98:99], v[108:109], v[104:105]
	v_pk_add_f32 v[82:83], v[82:83], v[86:87]
	v_pk_fma_f32 v[102:103], v[32:33], v[32:33], v[80:81] op_sel_hi:[1,1,0]
	v_mul_f32_e32 v80, v20, v20
	v_mul_f32_e32 v93, v21, v21
	v_pk_add_f32 v[86:87], v[98:99], v[98:99] op_sel:[0,1] op_sel_hi:[1,0]
	v_pk_add_f32 v[82:83], v[82:83], v[82:83] op_sel:[0,1] op_sel_hi:[1,0]
	v_mul_f32_e32 v106, v35, v35
	v_mov_b32_e32 v87, v93
	v_mov_b32_e32 v83, v80
	v_mul_f32_e32 v101, v23, v23
	v_pk_add_f32 v[82:83], v[82:83], v[86:87]
	v_pk_fma_f32 v[86:87], v[34:35], v[34:35], v[106:107] op_sel_hi:[1,1,0]
	v_mul_f32_e32 v103, v22, v22
	v_mov_b32_e32 v87, v101
	v_pk_add_f32 v[86:87], v[102:103], v[86:87]
	v_mul_f32_e32 v80, v16, v16
	v_pk_add_f32 v[82:83], v[82:83], v[86:87]
	v_mul_f32_e32 v86, v17, v17
	v_pk_add_f32 v[78:79], v[78:79], v[78:79] op_sel:[0,1] op_sel_hi:[1,0]
	v_pk_add_f32 v[84:85], v[84:85], v[84:85] op_sel:[0,1] op_sel_hi:[1,0]
	v_mov_b32_e32 v79, v80
	v_mov_b32_e32 v85, v86
	v_mul_f32_e32 v80, v29, v29
	v_mul_f32_e32 v87, v18, v18
	v_pk_add_f32 v[78:79], v[78:79], v[84:85]
	v_pk_fma_f32 v[84:85], v[28:29], v[28:29], v[80:81] op_sel_hi:[1,1,0]
	v_mul_f32_e32 v80, v31, v31
	v_mul_f32_e32 v93, v19, v19
	v_mov_b32_e32 v85, v87
	v_pk_fma_f32 v[86:87], v[30:31], v[30:31], v[80:81] op_sel_hi:[1,1,0]
	v_mul_f32_e32 v80, v24, v24
	v_mov_b32_e32 v87, v93
	v_pk_add_f32 v[84:85], v[84:85], v[86:87]
	v_pk_mul_f32 v[86:87], v[12:13], v[12:13]
	v_pk_add_f32 v[84:85], v[78:79], v[84:85]
	v_pk_mul_f32 v[78:79], v[14:15], v[14:15]
	v_pk_add_f32 v[82:83], v[82:83], v[82:83] op_sel:[0,1] op_sel_hi:[1,0]
	v_pk_mov_b32 v[98:99], v[86:87], v[78:79] op_sel:[1,0]
	v_mov_b32_e32 v87, v79
	v_pk_add_f32 v[78:79], v[98:99], v[86:87]
	v_pk_mul_f32 v[86:87], v[10:11], v[10:11]
	v_pk_mul_f32 v[98:99], v[8:9], v[8:9]
	v_pk_add_f32 v[78:79], v[78:79], v[78:79] op_sel:[0,1] op_sel_hi:[1,0]
	v_pk_mov_b32 v[100:101], v[98:99], v[86:87] op_sel:[1,0]
	v_mul_f32_e32 v86, v25, v25
	v_mov_b32_e32 v83, v80
	v_mov_b32_e32 v79, v86
	v_mul_f32_e32 v80, v37, v37
	v_mov_b32_e32 v99, v87
	v_mul_f32_e32 v87, v26, v26
	v_pk_add_f32 v[78:79], v[82:83], v[78:79]
	v_pk_fma_f32 v[82:83], v[36:37], v[36:37], v[80:81] op_sel_hi:[1,1,0]
	v_mul_f32_e32 v80, v39, v39
	v_mul_f32_e32 v93, v27, v27
	v_mov_b32_e32 v83, v87
	v_pk_fma_f32 v[86:87], v[38:39], v[38:39], v[80:81] op_sel_hi:[1,1,0]
	v_pk_add_f32 v[106:107], v[100:101], v[98:99]
	v_mov_b32_e32 v87, v93
	v_pk_add_f32 v[82:83], v[82:83], v[86:87]
	v_lshl_add_u64 v[86:87], s[16:17], 0, v[208:209]
	v_pk_add_f32 v[82:83], v[78:79], v[82:83]
	v_add_co_u32_e32 v78, vcc, s9, v86
	global_load_dwordx4 v[98:101], v[64:65], off
	s_nop 0
	v_addc_co_u32_e32 v79, vcc, 0, v87, vcc
	global_load_dwordx4 v[102:105], v[78:79], off offset:-4096
	v_mul_f32_e32 v80, v0, v0
	v_mul_f32_e32 v93, v1, v1
	v_pk_add_f32 v[84:85], v[84:85], v[84:85] op_sel:[0,1] op_sel_hi:[1,0]
	v_pk_add_f32 v[106:107], v[106:107], v[106:107] op_sel:[0,1] op_sel_hi:[1,0]
	v_mov_b32_e32 v85, v80
	v_mov_b32_e32 v107, v93
	v_mul_f32_e32 v80, v5, v5
	v_mul_f32_e32 v108, v2, v2
	v_pk_add_f32 v[84:85], v[84:85], v[106:107]
	v_pk_fma_f32 v[106:107], v[4:5], v[4:5], v[80:81] op_sel_hi:[1,1,0]
	v_mul_f32_e32 v80, v7, v7
	v_mul_f32_e32 v110, v3, v3
	v_mov_b32_e32 v107, v108
	v_pk_fma_f32 v[108:109], v[6:7], v[6:7], v[80:81] op_sel_hi:[1,1,0]
	s_waitcnt vmcnt(0)
; __device__ __forceinline__ unsigned cvt_pk_bf16(float lo, float hi) { unsigned r; asm volatile("v_cvt_pk_bf16_f32 %0, %1, %2" : "=v"(r) : "v"(lo), "v"(hi)); return r; }
; __device__ __forceinline__ void norm_rows(const float* xl, const float* xc, const float* g, const float* modl, int sh_ofs, int sc_ofs, bf16_t* XN, int nrows, int gw, int NGW) {
;     ...
;         const float rsa = rsqrtf(wave_sum(ssa) * (1.0f / DM) + EPS), rsb = rsqrtf(wave_sum(ssb) * (1.0f / DM) + EPS);
;         const f32x4* g4 = (const f32x4*)g + lane;
;         const f32x4* sca = (const f32x4*)(modl + (size_t)mia * 12288 + sc_ofs) + lane; const f32x4* sha = (const f32x4*)(modl + (size_t)mia * 12288 + sh_ofs) + lane;
;         const f32x4* scb = (const f32x4*)(modl + (size_t)mib * 12288 + sc_ofs) + lane; const f32x4* shb = (const f32x4*)(modl + (size_t)mib * 12288 + sh_ofs) + lane;
;         u32x2* oa = (u32x2*)(XN + (size_t)row * DM) + lane; u32x2* ob = (u32x2*)(XN + (size_t)rowb * DM) + lane;
; #pragma unroll
;         for (int j = 0; j < 8; ++j) { const f32x4 gj = g4[64 * j];
;             const f32x4 ya = va[j] * rsa * gj * (sca[64 * j] + 1.0f) + sha[64 * j]; u32x2 w; w.x = cvt_pk_bf16(ya[0], ya[1]); w.y = cvt_pk_bf16(ya[2], ya[3]); oa[64 * j] = w;
;             const f32x4 yb = vb[j] * rsb * gj * (scb[64 * j] + 1.0f) + shb[64 * j]; u32x2 w2; w2.x = cvt_pk_bf16(yb[0], yb[1]); w2.y = cvt_pk_bf16(yb[2], yb[3]); ob[64 * j] = w2; }
	v_pk_add_f32 v[102:103], v[102:103], 1.0 op_sel_hi:[1,0]
	v_mov_b32_e32 v109, v110
	v_pk_add_f32 v[106:107], v[106:107], v[108:109]
	s_nop 0
	v_pk_add_f32 v[84:85], v[84:85], v[106:107]
	v_mov_b32_e32 v107, v82
	v_mov_b32_e32 v106, v84
	v_mov_b32_e32 v82, v85
	v_pk_add_f32 v[82:83], v[106:107], v[82:83]
	ds_bpermute_b32 v85, v81, v83
	ds_bpermute_b32 v84, v81, v82
	s_waitcnt lgkmcnt(0)
	v_pk_add_f32 v[82:83], v[82:83], v[84:85]
	ds_bpermute_b32 v85, v88, v83
	ds_bpermute_b32 v84, v88, v82
	s_waitcnt lgkmcnt(0)
	v_pk_add_f32 v[82:83], v[82:83], v[84:85]
	ds_bpermute_b32 v85, v89, v83
	ds_bpermute_b32 v84, v89, v82
	s_waitcnt lgkmcnt(0)
	v_pk_add_f32 v[82:83], v[82:83], v[84:85]
	ds_bpermute_b32 v85, v90, v83
	ds_bpermute_b32 v84, v90, v82
	s_waitcnt lgkmcnt(0)
	v_pk_add_f32 v[82:83], v[82:83], v[84:85]
	ds_bpermute_b32 v85, v91, v83
	ds_bpermute_b32 v84, v91, v82
	s_waitcnt lgkmcnt(0)
	v_pk_add_f32 v[82:83], v[82:83], v[84:85]
	ds_bpermute_b32 v85, v92, v83
	ds_bpermute_b32 v84, v92, v82
	s_waitcnt lgkmcnt(0)
	v_pk_add_f32 v[82:83], v[82:83], v[84:85]
	s_nop 0
	v_pk_fma_f32 v[106:107], v[82:83], s[2:3], v[238:239] op_sel_hi:[1,0,0]
	s_mov_b32 s2, 0x800000
	v_mul_f32_e32 v80, 0x4b800000, v107
	v_cmp_gt_f32_e32 vcc, s2, v107
	v_lshl_add_u64 v[84:85], s[28:29], 0, v[208:209]
	s_nop 0
	v_cndmask_b32_e32 v80, v107, v80, vcc
	v_rsq_f32_e32 v80, v80
	s_nop 0
	v_mul_f32_e32 v82, 0x45800000, v80
	v_cndmask_b32_e32 v80, v80, v82, vcc
	v_pk_mul_f32 v[62:63], v[62:63], v[80:81] op_sel_hi:[1,0]
	v_pk_mul_f32 v[60:61], v[60:61], v[80:81] op_sel_hi:[1,0]
	v_pk_mul_f32 v[62:63], v[100:101], v[62:63]
	v_pk_mul_f32 v[60:61], v[98:99], v[60:61]
	v_pk_add_f32 v[82:83], v[104:105], 1.0 op_sel_hi:[1,0]
	v_pk_fma_f32 v[60:61], v[102:103], v[60:61], v[94:95]
	v_pk_fma_f32 v[62:63], v[82:83], v[62:63], v[96:97]
	v_add_co_u32_e32 v82, vcc, s9, v84
	v_cvt_pk_bf16_f32 v60, v60, v61
	v_cvt_pk_bf16_f32 v61, v62, v63
	global_store_dwordx2 v[76:77], v[60:61], off
	s_nop 0
	v_addc_co_u32_e32 v83, vcc, 0, v85, vcc
	global_load_dwordx4 v[94:97], v[82:83], off offset:-4096
	global_load_dwordx4 v[102:105], v208, s[28:29]
	v_mul_f32_e32 v60, 0x4b800000, v106
	v_cmp_gt_f32_e32 vcc, s2, v106
	v_pk_mul_f32 v[52:53], v[52:53], v[80:81] op_sel_hi:[1,0]
	v_pk_mul_f32 v[54:55], v[54:55], v[80:81] op_sel_hi:[1,0]
	v_cndmask_b32_e32 v60, v106, v60, vcc
	v_rsq_f32_e32 v62, v60
	v_lshl_add_u64 v[60:61], v[66:67], 0, s[14:15]
	s_mov_b64 s[14:15], 0x2000
	v_pk_mul_f32 v[44:45], v[44:45], v[80:81] op_sel_hi:[1,0]
	v_mul_f32_e32 v63, 0x45800000, v62
	v_cndmask_b32_e32 v62, v62, v63, vcc
	v_pk_mul_f32 v[56:57], v[56:57], v[62:63] op_sel_hi:[1,0]
	v_pk_mul_f32 v[58:59], v[58:59], v[62:63] op_sel_hi:[1,0]
	v_pk_mul_f32 v[56:57], v[98:99], v[56:57]
	v_pk_mul_f32 v[58:59], v[100:101], v[58:59]
	v_pk_mul_f32 v[48:49], v[48:49], v[62:63] op_sel_hi:[1,0]
	v_pk_mul_f32 v[50:51], v[50:51], v[62:63] op_sel_hi:[1,0]
	v_pk_mul_f32 v[46:47], v[46:47], v[80:81] op_sel_hi:[1,0]
	v_pk_mul_f32 v[40:41], v[40:41], v[62:63] op_sel_hi:[1,0]
	v_pk_mul_f32 v[42:43], v[42:43], v[62:63] op_sel_hi:[1,0]
	v_pk_mul_f32 v[32:33], v[32:33], v[80:81] op_sel_hi:[1,0]
	v_pk_mul_f32 v[34:35], v[34:35], v[80:81] op_sel_hi:[1,0]
	v_pk_mul_f32 v[28:29], v[28:29], v[62:63] op_sel_hi:[1,0]
	v_pk_mul_f32 v[30:31], v[30:31], v[62:63] op_sel_hi:[1,0]
	v_pk_mul_f32 v[20:21], v[20:21], v[80:81] op_sel_hi:[1,0]
	v_pk_mul_f32 v[22:23], v[22:23], v[80:81] op_sel_hi:[1,0]
	v_pk_mul_f32 v[16:17], v[16:17], v[62:63] op_sel_hi:[1,0]
	v_pk_mul_f32 v[18:19], v[18:19], v[62:63] op_sel_hi:[1,0]
	v_pk_mul_f32 v[12:13], v[12:13], v[80:81] op_sel_hi:[1,0]
	v_pk_mul_f32 v[14:15], v[14:15], v[80:81] op_sel_hi:[1,0]
	v_pk_mul_f32 v[8:9], v[8:9], v[62:63] op_sel_hi:[1,0]
	v_pk_mul_f32 v[10:11], v[10:11], v[62:63] op_sel_hi:[1,0]
	v_pk_mul_f32 v[6:7], v[6:7], v[62:63] op_sel_hi:[1,0]
	v_pk_mul_f32 v[4:5], v[4:5], v[62:63] op_sel_hi:[1,0]
	v_pk_mul_f32 v[2:3], v[2:3], v[62:63] op_sel_hi:[1,0]
	v_pk_mul_f32 v[0:1], v[0:1], v[62:63] op_sel_hi:[1,0]
	s_waitcnt vmcnt(1)
	v_pk_add_f32 v[94:95], v[94:95], 1.0 op_sel_hi:[1,0]
	v_pk_add_f32 v[96:97], v[96:97], 1.0 op_sel_hi:[1,0]
	s_waitcnt vmcnt(0)
	v_pk_fma_f32 v[56:57], v[94:95], v[56:57], v[102:103]
	v_pk_fma_f32 v[58:59], v[96:97], v[58:59], v[104:105]
	v_cvt_pk_bf16_f32 v56, v56, v57
	v_lshl_add_u64 v[102:103], v[86:87], 0, s[14:15]
	v_cvt_pk_bf16_f32 v57, v58, v59
	v_lshl_add_u64 v[246:247], v[84:85], 0, s[14:15]
	v_add_co_u32_e32 v248, vcc, s96, v86
	s_nop 1
	v_addc_co_u32_e32 v249, vcc, 0, v87, vcc
	v_add_co_u32_e32 v250, vcc, s96, v84
	s_nop 1
	v_addc_co_u32_e32 v251, vcc, 0, v85, vcc
	global_load_dwordx4 v[112:115], v[64:65], off offset:1024
	global_load_dwordx4 v[116:119], v[102:103], off offset:1024
	global_load_dwordx4 v[120:123], v208, s[16:17] offset:1024
	global_load_dwordx4 v[124:127], v[246:247], off offset:1024
	global_load_dwordx4 v[128:131], v208, s[28:29] offset:1024
	global_load_dwordx4 v[132:135], v[64:65], off offset:2048
	global_load_dwordx4 v[136:139], v[102:103], off offset:2048
	global_load_dwordx4 v[140:143], v208, s[16:17] offset:2048
	global_load_dwordx4 v[144:147], v[246:247], off offset:2048
	global_load_dwordx4 v[148:151], v208, s[28:29] offset:2048
	global_load_dwordx4 v[152:155], v[64:65], off offset:3072
	global_load_dwordx4 v[156:159], v[102:103], off offset:3072
	global_load_dwordx4 v[160:163], v208, s[16:17] offset:3072
	global_load_dwordx4 v[164:167], v[246:247], off offset:3072
	global_load_dwordx4 v[168:171], v208, s[28:29] offset:3072
	global_load_dwordx4 v[172:175], v[68:69], off
	global_load_dwordx4 v[176:179], v[78:79], off
	global_load_dwordx4 v[180:183], v[248:249], off
	global_load_dwordx4 v[184:187], v[82:83], off
	global_load_dwordx4 v[188:191], v[250:251], off
	global_load_dwordx4 v[192:195], v[70:71], off
	global_load_dwordx4 v[196:199], v[78:79], off offset:1024
	global_load_dwordx4 v[200:203], v[248:249], off offset:1024
	global_load_dwordx4 v[204:207], v[82:83], off offset:1024
	global_load_dwordx4 v[210:213], v[250:251], off offset:1024
	global_load_dwordx4 v[218:221], v[72:73], off
	global_load_dwordx4 v[222:225], v[78:79], off offset:2048
	global_load_dwordx4 v[226:229], v[248:249], off offset:2048
	global_load_dwordx4 v[230:233], v[82:83], off offset:2048
	global_load_dwordx4 v[234:237], v[250:251], off offset:2048
	global_store_dwordx2 v[60:61], v[56:57], off
	s_waitcnt vmcnt(1)
; __device__ __forceinline__ unsigned cvt_pk_bf16(float lo, float hi) { unsigned r; asm volatile("v_cvt_pk_bf16_f32 %0, %1, %2" : "=v"(r) : "v"(lo), "v"(hi)); return r; }
; __device__ __forceinline__ void norm_rows(const float* xl, const float* xc, const float* g, const float* modl, int sh_ofs, int sc_ofs, bf16_t* XN, int nrows, int gw, int NGW) {
;     ...
;         for (int j = 0; j < 8; ++j) { const f32x4 gj = g4[64 * j];
;             const f32x4 ya = va[j] * rsa * gj * (sca[64 * j] + 1.0f) + sha[64 * j]; u32x2 w; w.x = cvt_pk_bf16(ya[0], ya[1]); w.y = cvt_pk_bf16(ya[2], ya[3]); oa[64 * j] = w;
;             const f32x4 yb = vb[j] * rsb * gj * (scb[64 * j] + 1.0f) + shb[64 * j]; u32x2 w2; w2.x = cvt_pk_bf16(yb[0], yb[1]); w2.y = cvt_pk_bf16(yb[2], yb[3]); ob[64 * j] = w2; }
	s_nop 0
	s_nop 0
	s_nop 0
	s_nop 0
	v_lshl_add_u64 v[104:105], v[84:85], 0, s[14:15]
	v_readlane_b32 s14, v254, 45
	v_readlane_b32 s15, v254, 46
	s_nop 0
	v_pk_mul_f32 v[52:53], v[52:53], v[112:113]
	s_nop 0
	v_pk_add_f32 v[94:95], v[116:117], 1.0 op_sel_hi:[1, 0]
	v_pk_mul_f32 v[54:55], v[54:55], v[114:115]
	v_pk_add_f32 v[96:97], v[118:119], 1.0 op_sel_hi:[1, 0]
	s_nop 0
	v_pk_fma_f32 v[52:53], v[52:53], v[94:95], v[120:121]
	v_pk_fma_f32 v[54:55], v[54:55], v[96:97], v[122:123]
	v_cvt_pk_bf16_f32 v52, v52, v53
	v_pk_mul_f32 v[48:49], v[112:113], v[48:49]
	v_cvt_pk_bf16_f32 v53, v54, v55
	global_store_dwordx2 v[76:77], v[52:53], off offset:512
	s_nop 0
	s_nop 0
	s_nop 0
	v_pk_mul_f32 v[50:51], v[114:115], v[50:51]
	s_nop 0
	v_pk_add_f32 v[52:53], v[124:125], 1.0 op_sel_hi:[1, 0]
	v_pk_add_f32 v[54:55], v[126:127], 1.0 op_sel_hi:[1, 0]
	s_nop 0
	v_pk_fma_f32 v[48:49], v[48:49], v[52:53], v[128:129]
	v_pk_fma_f32 v[50:51], v[50:51], v[54:55], v[130:131]
	v_cvt_pk_bf16_f32 v48, v48, v49
	s_nop 0
	v_cvt_pk_bf16_f32 v49, v50, v51
	global_store_dwordx2 v[60:61], v[48:49], off offset:512
	global_load_dwordx4 v[112:115], v[74:75], off
	global_load_dwordx4 v[116:119], v[78:79], off offset:3072
	global_load_dwordx4 v[120:123], v[248:249], off offset:3072
	global_load_dwordx4 v[124:127], v[82:83], off offset:3072
	global_load_dwordx4 v[128:131], v[250:251], off offset:3072
	s_nop 0
	s_nop 0
	s_nop 0
	s_nop 0
	s_nop 0
	v_pk_mul_f32 v[44:45], v[44:45], v[132:133]
	s_nop 0
	v_pk_add_f32 v[52:53], v[136:137], 1.0 op_sel_hi:[1, 0]
	v_pk_mul_f32 v[46:47], v[46:47], v[134:135]
	v_pk_add_f32 v[54:55], v[138:139], 1.0 op_sel_hi:[1, 0]
	s_nop 0
	v_pk_fma_f32 v[44:45], v[44:45], v[52:53], v[140:141]
	v_pk_fma_f32 v[46:47], v[46:47], v[54:55], v[142:143]
	v_cvt_pk_bf16_f32 v44, v44, v45
	v_pk_mul_f32 v[40:41], v[40:41], v[132:133]
	v_cvt_pk_bf16_f32 v45, v46, v47
	global_store_dwordx2 v[76:77], v[44:45], off offset:1024
	s_nop 0
	s_nop 0
	s_nop 0
	v_pk_mul_f32 v[42:43], v[42:43], v[134:135]
	s_nop 0
	v_pk_add_f32 v[44:45], v[144:145], 1.0 op_sel_hi:[1, 0]
	v_pk_add_f32 v[46:47], v[146:147], 1.0 op_sel_hi:[1, 0]
	s_nop 0
	v_pk_fma_f32 v[40:41], v[40:41], v[44:45], v[148:149]
	v_pk_fma_f32 v[42:43], v[42:43], v[46:47], v[150:151]
	v_cvt_pk_bf16_f32 v40, v40, v41
	s_nop 0
	v_cvt_pk_bf16_f32 v41, v42, v43
	global_store_dwordx2 v[60:61], v[40:41], off offset:1024
	s_nop 0
	s_nop 0
	s_nop 0
	s_nop 0
	s_nop 0
	v_pk_mul_f32 v[32:33], v[32:33], v[152:153]
	s_nop 0
	v_pk_add_f32 v[44:45], v[156:157], 1.0 op_sel_hi:[1, 0]
	v_pk_mul_f32 v[34:35], v[34:35], v[154:155]
	v_pk_add_f32 v[46:47], v[158:159], 1.0 op_sel_hi:[1, 0]
	s_nop 0
	v_pk_fma_f32 v[32:33], v[32:33], v[44:45], v[160:161]
	v_pk_fma_f32 v[34:35], v[34:35], v[46:47], v[162:163]
	v_cvt_pk_bf16_f32 v32, v32, v33
	v_pk_mul_f32 v[28:29], v[28:29], v[152:153]
	v_cvt_pk_bf16_f32 v33, v34, v35
	global_store_dwordx2 v[76:77], v[32:33], off offset:1536
	s_nop 0
	s_nop 0
	s_nop 0
	v_pk_mul_f32 v[30:31], v[30:31], v[154:155]
	s_nop 0
	v_pk_add_f32 v[32:33], v[164:165], 1.0 op_sel_hi:[1, 0]
	v_pk_add_f32 v[34:35], v[166:167], 1.0 op_sel_hi:[1, 0]
	s_nop 0
	v_pk_fma_f32 v[28:29], v[28:29], v[32:33], v[168:169]
	v_pk_fma_f32 v[30:31], v[30:31], v[34:35], v[170:171]
	v_cvt_pk_bf16_f32 v28, v28, v29
	v_add_co_u32_e32 v44, vcc, s96, v86
	v_cvt_pk_bf16_f32 v29, v30, v31
	global_store_dwordx2 v[60:61], v[28:29], off offset:1536
	s_nop 0
	s_nop 0
	s_nop 0
	v_addc_co_u32_e32 v45, vcc, 0, v87, vcc
	s_nop 0
	s_nop 0
	v_pk_mul_f32 v[20:21], v[20:21], v[172:173]
	s_nop 0
	v_pk_add_f32 v[32:33], v[176:177], 1.0 op_sel_hi:[1, 0]
	v_pk_mul_f32 v[22:23], v[22:23], v[174:175]
	v_pk_add_f32 v[34:35], v[178:179], 1.0 op_sel_hi:[1, 0]
	s_nop 0
	v_pk_fma_f32 v[20:21], v[20:21], v[32:33], v[180:181]
	v_pk_fma_f32 v[22:23], v[22:23], v[34:35], v[182:183]
	v_cvt_pk_bf16_f32 v20, v20, v21
	v_add_co_u32_e32 v40, vcc, s96, v84
	v_cvt_pk_bf16_f32 v21, v22, v23
	global_store_dwordx2 v[76:77], v[20:21], off offset:2048
	s_nop 0
	v_addc_co_u32_e32 v41, vcc, 0, v85, vcc
	s_nop 0
	v_pk_mul_f32 v[16:17], v[16:17], v[172:173]
	v_pk_mul_f32 v[18:19], v[18:19], v[174:175]
	s_nop 0
	v_pk_add_f32 v[20:21], v[184:185], 1.0 op_sel_hi:[1, 0]
	v_pk_add_f32 v[22:23], v[186:187], 1.0 op_sel_hi:[1, 0]
	s_nop 0
	v_pk_fma_f32 v[16:17], v[16:17], v[20:21], v[188:189]
	v_pk_fma_f32 v[18:19], v[18:19], v[22:23], v[190:191]
	v_cvt_pk_bf16_f32 v16, v16, v17
	s_nop 0
	v_cvt_pk_bf16_f32 v17, v18, v19
	global_store_dwordx2 v[60:61], v[16:17], off offset:2048
	s_nop 0
	s_nop 0
	s_nop 0
	s_nop 0
	s_nop 0
	v_pk_mul_f32 v[12:13], v[12:13], v[192:193]
	s_nop 0
	v_pk_add_f32 v[20:21], v[196:197], 1.0 op_sel_hi:[1, 0]
	v_pk_mul_f32 v[14:15], v[14:15], v[194:195]
	v_pk_add_f32 v[22:23], v[198:199], 1.0 op_sel_hi:[1, 0]
	s_nop 0
	v_pk_fma_f32 v[12:13], v[12:13], v[20:21], v[200:201]
	v_pk_fma_f32 v[14:15], v[14:15], v[22:23], v[202:203]
	v_cvt_pk_bf16_f32 v12, v12, v13
	v_pk_mul_f32 v[8:9], v[8:9], v[192:193]
	v_cvt_pk_bf16_f32 v13, v14, v15
	global_store_dwordx2 v[76:77], v[12:13], off offset:2560
	s_nop 0
	s_nop 0
	s_nop 0
	v_pk_mul_f32 v[10:11], v[10:11], v[194:195]
	s_nop 0
	v_pk_add_f32 v[12:13], v[204:205], 1.0 op_sel_hi:[1, 0]
	v_pk_add_f32 v[14:15], v[206:207], 1.0 op_sel_hi:[1, 0]
	s_nop 0
	v_pk_fma_f32 v[8:9], v[8:9], v[12:13], v[210:211]
	v_pk_fma_f32 v[10:11], v[10:11], v[14:15], v[212:213]
	v_cvt_pk_bf16_f32 v8, v8, v9
	v_pk_mul_f32 v[22:23], v[36:37], v[80:81] op_sel_hi:[1, 0]
	v_cvt_pk_bf16_f32 v9, v10, v11
	global_store_dwordx2 v[60:61], v[8:9], off offset:2560
	s_nop 0
	s_nop 0
	s_nop 0
	s_nop 0
	v_pk_mul_f32 v[20:21], v[38:39], v[80:81] op_sel_hi:[1, 0]
	s_nop 0
	v_pk_mul_f32 v[22:23], v[22:23], v[218:219]
	s_nop 0
	v_pk_add_f32 v[12:13], v[222:223], 1.0 op_sel_hi:[1, 0]
	v_pk_mul_f32 v[20:21], v[20:21], v[220:221]
	v_pk_add_f32 v[14:15], v[224:225], 1.0 op_sel_hi:[1, 0]
	s_nop 0
	v_pk_fma_f32 v[12:13], v[22:23], v[12:13], v[226:227]
	v_pk_fma_f32 v[14:15], v[20:21], v[14:15], v[228:229]
	v_cvt_pk_bf16_f32 v12, v12, v13
	v_pk_mul_f32 v[4:5], v[4:5], v[218:219]
	v_cvt_pk_bf16_f32 v13, v14, v15
	global_store_dwordx2 v[76:77], v[12:13], off offset:3072
	s_nop 0
	s_nop 0
	s_nop 0
	v_pk_mul_f32 v[6:7], v[6:7], v[220:221]
	s_nop 0
	v_pk_add_f32 v[10:11], v[230:231], 1.0 op_sel_hi:[1, 0]
	v_pk_add_f32 v[8:9], v[232:233], 1.0 op_sel_hi:[1, 0]
	s_nop 0
	v_pk_fma_f32 v[4:5], v[4:5], v[10:11], v[234:235]
	v_pk_fma_f32 v[6:7], v[6:7], v[8:9], v[236:237]
	v_cvt_pk_bf16_f32 v4, v4, v5
	v_pk_mul_f32 v[18:19], v[24:25], v[80:81] op_sel_hi:[1, 0]
	v_cvt_pk_bf16_f32 v5, v6, v7
	global_store_dwordx2 v[60:61], v[4:5], off offset:3072
	s_nop 0
	s_nop 0
	s_nop 0
	s_nop 0
	v_pk_mul_f32 v[16:17], v[26:27], v[80:81] op_sel_hi:[1, 0]
	s_waitcnt vmcnt(0)
; __device__ __forceinline__ unsigned cvt_pk_bf16(float lo, float hi) { unsigned r; asm volatile("v_cvt_pk_bf16_f32 %0, %1, %2" : "=v"(r) : "v"(lo), "v"(hi)); return r; }
; __device__ __forceinline__ void norm_rows(const float* xl, const float* xc, const float* g, const float* modl, int sh_ofs, int sc_ofs, bf16_t* XN, int nrows, int gw, int NGW) {
;     ...
;         for (int j = 0; j < 8; ++j) { const f32x4 gj = g4[64 * j];
;             const f32x4 ya = va[j] * rsa * gj * (sca[64 * j] + 1.0f) + sha[64 * j]; u32x2 w; w.x = cvt_pk_bf16(ya[0], ya[1]); w.y = cvt_pk_bf16(ya[2], ya[3]); oa[64 * j] = w;
;             const f32x4 yb = vb[j] * rsb * gj * (scb[64 * j] + 1.0f) + shb[64 * j]; u32x2 w2; w2.x = cvt_pk_bf16(yb[0], yb[1]); w2.y = cvt_pk_bf16(yb[2], yb[3]); ob[64 * j] = w2; }
	v_pk_mul_f32 v[18:19], v[18:19], v[112:113]
	s_nop 0
	v_pk_add_f32 v[8:9], v[116:117], 1.0 op_sel_hi:[1, 0]
	v_pk_mul_f32 v[16:17], v[16:17], v[114:115]
	v_pk_add_f32 v[10:11], v[118:119], 1.0 op_sel_hi:[1, 0]
	s_nop 0
	v_pk_fma_f32 v[8:9], v[18:19], v[8:9], v[120:121]
	v_pk_fma_f32 v[10:11], v[16:17], v[10:11], v[122:123]
	v_cvt_pk_bf16_f32 v8, v8, v9
	v_pk_mul_f32 v[0:1], v[0:1], v[112:113]
	v_cvt_pk_bf16_f32 v9, v10, v11
	global_store_dwordx2 v[76:77], v[8:9], off offset:3584
	s_nop 0
	s_nop 0
	s_nop 0
	v_pk_mul_f32 v[2:3], v[2:3], v[114:115]
	v_lshl_add_u64 v[76:77], v[76:77], 0, s[14:15]
	s_nop 0
	v_pk_add_f32 v[6:7], v[124:125], 1.0 op_sel_hi:[1, 0]
	v_pk_add_f32 v[4:5], v[126:127], 1.0 op_sel_hi:[1, 0]
	s_nop 0
	v_pk_fma_f32 v[0:1], v[0:1], v[6:7], v[128:129]
	v_pk_fma_f32 v[2:3], v[2:3], v[4:5], v[130:131]
	v_cvt_pk_bf16_f32 v0, v0, v1
	s_nop 0
	v_cvt_pk_bf16_f32 v1, v2, v3
	global_store_dwordx2 v[60:61], v[0:1], off offset:3584
	s_cbranch_scc1 .LBB0_506
